# MLA and GEMM loop heads aligned to 64 bytes (s_nop padding), on top of v28
# baseline (speedup 1.0000x reference)
; __device__ __forceinline__ float bf2f(unsigned h) { return __uint_as_float(h << 16); }
; __device__ __forceinline__ void mla_unit(char* lds, const bf16_t* __restrict__ Qp, const bf16_t* __restrict__ Knp, const bf16_t* __restrict__ Vp, ...
;     ...
;   const bf16_t* Qw = Qp + (long)(wid * QBLK + r32) * LDQ + hi * 8;
; #pragma unroll
;   for (int d0 = 0; d0 < 8; ++d0) { const u32x4 raw = *reinterpret_cast<const u32x4*>(Qw + d0 * 16); u32x4 w;
; #pragma unroll
;     for (int p = 0; p < 4; ++p) w[p] = cvtpk(bf2f(raw[p] & 0xffffu) * C, bf2f(raw[p] >> 16) * C);
;     qr[d0] = *reinterpret_cast<bf16x8*>(&w); }
.LBB0_238:
	s_lshl_b32 s1, s74, 8
	s_lshl_b64 s[64:65], s[6:7], 13
	s_and_b32 s1, s1, 0x1f00
	s_or_b32 s64, s64, s1
	s_mul_hi_u32 s6, s64, 0x1800
	s_mul_i32 s7, s65, 0x1800
	s_mul_i32 s5, s64, 0x1800
	s_add_i32 s6, s6, s7
	v_readlane_b32 s7, v254, 60
	s_add_u32 s5, s7, s5
	v_readlane_b32 s7, v254, 61
	s_addc_u32 s7, s7, s6
	s_mul_i32 s6, s38, 0x180
	s_add_u32 s6, s5, s6
	s_addc_u32 s7, s7, 0
	v_and_b32_e32 v196, 31, v50
	s_lshl_b32 s39, s8, 5
	v_or_b32_e32 v1, s39, v196
	v_mov_b64_e32 v[2:3], s[6:7]
	s_movk_i32 s5, 0x1800
	v_mad_i64_i32 v[2:3], s[6:7], v1, s5, v[2:3]
	v_lshlrev_b32_e32 v194, 4, v49
	v_mov_b32_e32 v195, v0
	v_lshl_add_u64 v[2:3], v[2:3], 0, v[194:195]
	global_load_dwordx4 v[130:133], v[2:3], off
	global_load_dwordx4 v[134:137], v[2:3], off offset:32
	global_load_dwordx4 v[138:141], v[2:3], off offset:64
	global_load_dwordx4 v[142:145], v[2:3], off offset:96
	global_load_dwordx4 v[154:157], v[2:3], off offset:128
	global_load_dwordx4 v[150:153], v[2:3], off offset:160
	global_load_dwordx4 v[146:149], v[2:3], off offset:192
	global_load_dwordx4 v[158:161], v[2:3], off offset:224
	global_load_dwordx4 v[162:165], v[2:3], off offset:256
	global_load_dwordx4 v[166:169], v[2:3], off offset:288
	global_load_dwordx4 v[170:173], v[2:3], off offset:320
	global_load_dwordx4 v[174:177], v[2:3], off offset:352
	s_mov_b32 s6, 0x3dd53b94
	v_lshlrev_b32_e32 v204, 8, v196
	v_and_b32_e32 v51, 0xf0, v48
	v_add_u32_e32 v66, 0, v204
	s_waitcnt vmcnt(20)
	v_xad_u32 v56, v194, v51, v66
	v_lshlrev_b32_e32 v205, 7, v196
	s_and_b32 s0, s0, 0x3fffffc0
	s_lshl_b32 s0, s0, 2
	s_add_i32 s33, s0, 0
	s_add_i32 s33, s33, 0x1e000
	v_lshl_add_u32 v200, v196, 2, s33
	s_waitcnt vmcnt(11)
	v_lshlrev_b32_e32 v1, 16, v130
	v_and_b32_e32 v4, 0xffff0000, v130
	v_lshlrev_b32_e32 v8, 16, v131
	v_and_b32_e32 v5, 0xffff0000, v131
	v_lshlrev_b32_e32 v9, 16, v132
	v_and_b32_e32 v6, 0xffff0000, v132
	v_lshlrev_b32_e32 v10, 16, v133
	v_and_b32_e32 v7, 0xffff0000, v133
	v_mul_f32_e32 v4, 0x3dd53b94, v4
	v_mul_f32_e32 v5, 0x3dd53b94, v5
	v_mul_f32_e32 v6, 0x3dd53b94, v6
	v_mul_f32_e32 v7, 0x3dd53b94, v7
	v_mul_f32_e32 v1, 0x3dd53b94, v1
	v_mul_f32_e32 v8, 0x3dd53b94, v8
	v_mul_f32_e32 v9, 0x3dd53b94, v9
	v_mul_f32_e32 v10, 0x3dd53b94, v10
	v_cvt_pk_bf16_f32 v130, v1, v4
	v_cvt_pk_bf16_f32 v131, v8, v5
	v_cvt_pk_bf16_f32 v132, v9, v6
	v_cvt_pk_bf16_f32 v133, v10, v7
	s_waitcnt vmcnt(10)
	v_lshlrev_b32_e32 v1, 16, v134
	v_and_b32_e32 v4, 0xffff0000, v134
	v_lshlrev_b32_e32 v8, 16, v135
	v_and_b32_e32 v5, 0xffff0000, v135
	v_lshlrev_b32_e32 v9, 16, v136
	v_and_b32_e32 v6, 0xffff0000, v136
	v_lshlrev_b32_e32 v10, 16, v137
	v_and_b32_e32 v7, 0xffff0000, v137
	v_mul_f32_e32 v4, 0x3dd53b94, v4
	v_mul_f32_e32 v5, 0x3dd53b94, v5
	v_mul_f32_e32 v6, 0x3dd53b94, v6
	v_mul_f32_e32 v7, 0x3dd53b94, v7
	v_mul_f32_e32 v1, 0x3dd53b94, v1
	v_mul_f32_e32 v8, 0x3dd53b94, v8
	v_mul_f32_e32 v9, 0x3dd53b94, v9
	v_mul_f32_e32 v10, 0x3dd53b94, v10
	v_cvt_pk_bf16_f32 v134, v1, v4
	v_cvt_pk_bf16_f32 v135, v8, v5
	v_cvt_pk_bf16_f32 v136, v9, v6
	v_cvt_pk_bf16_f32 v137, v10, v7
	s_waitcnt vmcnt(9)
	v_lshlrev_b32_e32 v1, 16, v138
	v_and_b32_e32 v4, 0xffff0000, v138
	v_lshlrev_b32_e32 v8, 16, v139
	v_and_b32_e32 v5, 0xffff0000, v139
	v_lshlrev_b32_e32 v9, 16, v140
	v_and_b32_e32 v6, 0xffff0000, v140
	v_lshlrev_b32_e32 v10, 16, v141
	v_and_b32_e32 v7, 0xffff0000, v141
	v_mul_f32_e32 v4, 0x3dd53b94, v4
	v_mul_f32_e32 v5, 0x3dd53b94, v5
	v_mul_f32_e32 v6, 0x3dd53b94, v6
	v_mul_f32_e32 v7, 0x3dd53b94, v7
	v_mul_f32_e32 v1, 0x3dd53b94, v1
	v_mul_f32_e32 v8, 0x3dd53b94, v8
	v_mul_f32_e32 v9, 0x3dd53b94, v9
	v_mul_f32_e32 v10, 0x3dd53b94, v10
	v_cvt_pk_bf16_f32 v138, v1, v4
	v_cvt_pk_bf16_f32 v139, v8, v5
	v_cvt_pk_bf16_f32 v140, v9, v6
	v_cvt_pk_bf16_f32 v141, v10, v7
	s_waitcnt vmcnt(8)
	v_lshlrev_b32_e32 v1, 16, v142
	v_and_b32_e32 v4, 0xffff0000, v142
	v_lshlrev_b32_e32 v8, 16, v143
	v_and_b32_e32 v5, 0xffff0000, v143
	v_lshlrev_b32_e32 v9, 16, v144
	v_and_b32_e32 v6, 0xffff0000, v144
	v_lshlrev_b32_e32 v10, 16, v145
	v_and_b32_e32 v7, 0xffff0000, v145
	v_mul_f32_e32 v4, 0x3dd53b94, v4
	v_mul_f32_e32 v5, 0x3dd53b94, v5
	v_mul_f32_e32 v6, 0x3dd53b94, v6
	v_mul_f32_e32 v7, 0x3dd53b94, v7
	v_mul_f32_e32 v1, 0x3dd53b94, v1
	v_mul_f32_e32 v8, 0x3dd53b94, v8
	v_mul_f32_e32 v9, 0x3dd53b94, v9
	v_mul_f32_e32 v10, 0x3dd53b94, v10
	v_cvt_pk_bf16_f32 v142, v1, v4
	v_cvt_pk_bf16_f32 v143, v8, v5
	v_cvt_pk_bf16_f32 v144, v9, v6
	v_cvt_pk_bf16_f32 v145, v10, v7
	s_waitcnt vmcnt(7)
	v_lshlrev_b32_e32 v1, 16, v154
	v_and_b32_e32 v4, 0xffff0000, v154
	v_lshlrev_b32_e32 v8, 16, v155
	v_and_b32_e32 v5, 0xffff0000, v155
	v_lshlrev_b32_e32 v9, 16, v156
	v_and_b32_e32 v6, 0xffff0000, v156
	v_lshlrev_b32_e32 v10, 16, v157
	v_and_b32_e32 v7, 0xffff0000, v157
	v_mul_f32_e32 v4, 0x3dd53b94, v4
	v_mul_f32_e32 v5, 0x3dd53b94, v5
	v_mul_f32_e32 v6, 0x3dd53b94, v6
	v_mul_f32_e32 v7, 0x3dd53b94, v7
	v_mul_f32_e32 v1, 0x3dd53b94, v1
	v_mul_f32_e32 v8, 0x3dd53b94, v8
	v_mul_f32_e32 v9, 0x3dd53b94, v9
	v_mul_f32_e32 v10, 0x3dd53b94, v10
	v_cvt_pk_bf16_f32 v154, v1, v4
	v_cvt_pk_bf16_f32 v155, v8, v5
	v_cvt_pk_bf16_f32 v156, v9, v6
	v_cvt_pk_bf16_f32 v157, v10, v7
	s_waitcnt vmcnt(6)
	v_lshlrev_b32_e32 v1, 16, v150
	v_and_b32_e32 v4, 0xffff0000, v150
	v_lshlrev_b32_e32 v8, 16, v151
	v_and_b32_e32 v5, 0xffff0000, v151
	v_lshlrev_b32_e32 v9, 16, v152
	v_and_b32_e32 v6, 0xffff0000, v152
	v_lshlrev_b32_e32 v10, 16, v153
	v_and_b32_e32 v7, 0xffff0000, v153
	v_mul_f32_e32 v4, 0x3dd53b94, v4
	v_mul_f32_e32 v5, 0x3dd53b94, v5
	v_mul_f32_e32 v6, 0x3dd53b94, v6
	v_mul_f32_e32 v7, 0x3dd53b94, v7
	v_mul_f32_e32 v1, 0x3dd53b94, v1
	v_mul_f32_e32 v8, 0x3dd53b94, v8
	v_mul_f32_e32 v9, 0x3dd53b94, v9
	v_mul_f32_e32 v10, 0x3dd53b94, v10
	v_cvt_pk_bf16_f32 v150, v1, v4
	v_cvt_pk_bf16_f32 v151, v8, v5
	v_cvt_pk_bf16_f32 v152, v9, v6
	v_cvt_pk_bf16_f32 v153, v10, v7
	s_waitcnt vmcnt(5)
; __device__ __forceinline__ float bf2f(unsigned h) { return __uint_as_float(h << 16); }
; __device__ __forceinline__ void mla_unit(char* lds, const bf16_t* __restrict__ Qp, const bf16_t* __restrict__ Knp, const bf16_t* __restrict__ Vp, ...
;     ...
;   for (int d0 = 0; d0 < 8; ++d0) { const u32x4 raw = *reinterpret_cast<const u32x4*>(Qw + d0 * 16); u32x4 w;
; #pragma unroll
;     for (int p = 0; p < 4; ++p) w[p] = cvtpk(bf2f(raw[p] & 0xffffu) * C, bf2f(raw[p] >> 16) * C);
;     qr[d0] = *reinterpret_cast<bf16x8*>(&w); }
;   { const int pos = pos0 + wid * QBLK + r32;
; #pragma unroll
;     for (int d0 = 0; d0 < 4; ++d0) {
;       const u32x4 raw = *reinterpret_cast<const u32x4*>(Qw + 128 + d0 * 16);
;       const int i0 = d0 * 8 + hi * 4;
;       const f32x4 cc = *reinterpret_cast<const f32x4*>(cs_tab + pos * 32 + i0) * C, ss = *reinterpret_cast<const f32x4*>(sn_tab + pos * 32 + i0) * C;
;       u32x4 w;
; #pragma unroll
;       for (int p = 0; p < 4; ++p) { const float x1 = bf2f(raw[p] & 0xffffu), x2 = bf2f(raw[p] >> 16); w[p] = cvtpk(x1 * cc[p] - x2 * ss[p], x1 * ss[p] + x2 * cc[p]); }
;       qr[8 + d0] = *reinterpret_cast<bf16x8*>(&w);
;     } }
	v_lshlrev_b32_e32 v8, 16, v147
	v_lshlrev_b32_e32 v9, 16, v148
	v_and_b32_e32 v6, 0xffff0000, v148
	v_lshlrev_b32_e32 v10, 16, v149
	v_and_b32_e32 v7, 0xffff0000, v149
	v_lshlrev_b32_e32 v1, 16, v146
	v_and_b32_e32 v4, 0xffff0000, v146
	v_and_b32_e32 v5, 0xffff0000, v147
	v_mul_f32_e32 v8, 0x3dd53b94, v8
	v_mul_f32_e32 v9, 0x3dd53b94, v9
	v_mul_f32_e32 v6, 0x3dd53b94, v6
	v_mul_f32_e32 v7, 0x3dd53b94, v7
	v_mul_f32_e32 v1, 0x3dd53b94, v1
	v_mul_f32_e32 v4, 0x3dd53b94, v4
	v_mul_f32_e32 v5, 0x3dd53b94, v5
	v_mul_f32_e32 v10, 0x3dd53b94, v10
	v_cvt_pk_bf16_f32 v146, v1, v4
	v_cvt_pk_bf16_f32 v147, v8, v5
	v_cvt_pk_bf16_f32 v148, v9, v6
	v_cvt_pk_bf16_f32 v149, v10, v7
	v_or_b32_e32 v1, s1, v196
	v_add_lshl_u32 v4, v1, s39, 5
	v_ashrrev_i32_e32 v5, 31, v4
	v_lshlrev_b64 v[4:5], 2, v[4:5]
	v_lshl_add_u64 v[10:11], s[34:35], 0, v[4:5]
	v_lshl_add_u64 v[12:13], s[86:87], 0, v[4:5]
	v_lshl_add_u64 v[4:5], v[10:11], 0, v[194:195]
	v_lshl_add_u64 v[18:19], v[12:13], 0, v[194:195]
	s_add_i32 s1, 0, 0x18000
	v_add_u32_e32 v206, s1, v205
	s_waitcnt vmcnt(4)
	v_lshlrev_b32_e32 v1, 16, v158
	v_and_b32_e32 v6, 0xffff0000, v158
	v_lshlrev_b32_e32 v10, 16, v159
	v_and_b32_e32 v7, 0xffff0000, v159
	v_lshlrev_b32_e32 v11, 16, v160
	v_and_b32_e32 v8, 0xffff0000, v160
	v_lshlrev_b32_e32 v14, 16, v161
	v_and_b32_e32 v9, 0xffff0000, v161
	v_mul_f32_e32 v6, 0x3dd53b94, v6
	v_mul_f32_e32 v10, 0x3dd53b94, v10
	v_mul_f32_e32 v7, 0x3dd53b94, v7
	v_mul_f32_e32 v11, 0x3dd53b94, v11
	v_mul_f32_e32 v8, 0x3dd53b94, v8
	v_mul_f32_e32 v14, 0x3dd53b94, v14
	v_mul_f32_e32 v9, 0x3dd53b94, v9
	v_mul_f32_e32 v1, 0x3dd53b94, v1
	v_cvt_pk_bf16_f32 v158, v1, v6
	v_cvt_pk_bf16_f32 v159, v10, v7
	v_cvt_pk_bf16_f32 v160, v11, v8
	v_cvt_pk_bf16_f32 v161, v14, v9
	global_load_dwordx4 v[10:13], v[4:5], off
	global_load_dwordx4 v[14:17], v[18:19], off
	s_waitcnt vmcnt(1)
	v_mov_b32_e32 v22, v10
	s_waitcnt vmcnt(0)
	v_mov_b32_e32 v23, v14
	v_mov_b32_e32 v14, v11
	v_mov_b32_e32 v24, v12
	v_mov_b32_e32 v25, v16
	v_mov_b32_e32 v16, v13
	v_lshlrev_b32_e32 v20, 16, v162
	v_and_b32_e32 v21, 0xffff0000, v162
	v_lshlrev_b32_e32 v6, 16, v163
	v_and_b32_e32 v7, 0xffff0000, v163
	v_lshlrev_b32_e32 v10, 16, v164
	v_and_b32_e32 v11, 0xffff0000, v164
	v_lshlrev_b32_e32 v8, 16, v165
	v_and_b32_e32 v9, 0xffff0000, v165
	v_pk_mul_f32 v[12:13], v[22:23], s[6:7] op_sel_hi:[1,0]
	v_pk_mul_f32 v[14:15], v[14:15], s[6:7] op_sel_hi:[1,0]
	v_pk_mul_f32 v[22:23], v[24:25], s[6:7] op_sel_hi:[1,0]
	v_pk_mul_f32 v[16:17], v[16:17], s[6:7] op_sel_hi:[1,0]
	v_pk_mul_f32 v[24:25], v[12:13], v[20:21]
	v_pk_mul_f32 v[12:13], v[12:13], v[20:21] op_sel:[0,1] op_sel_hi:[1,0]
	v_pk_mul_f32 v[20:21], v[14:15], v[6:7]
	v_pk_mul_f32 v[6:7], v[14:15], v[6:7] op_sel:[0,1] op_sel_hi:[1,0]
	v_pk_mul_f32 v[14:15], v[22:23], v[10:11]
	v_pk_mul_f32 v[10:11], v[22:23], v[10:11] op_sel:[0,1] op_sel_hi:[1,0]
	v_pk_mul_f32 v[22:23], v[16:17], v[8:9]
	v_pk_mul_f32 v[8:9], v[16:17], v[8:9] op_sel:[0,1] op_sel_hi:[1,0]
	v_add_f32_e32 v12, v12, v13
	v_sub_f32_e32 v13, v20, v21
	v_add_f32_e32 v6, v6, v7
	v_sub_f32_e32 v7, v14, v15
	v_add_f32_e32 v10, v10, v11
	v_sub_f32_e32 v11, v22, v23
	v_add_f32_e32 v8, v8, v9
	v_sub_f32_e32 v1, v24, v25
	v_cvt_pk_bf16_f32 v162, v1, v12
	v_cvt_pk_bf16_f32 v163, v13, v6
	v_cvt_pk_bf16_f32 v164, v7, v10
	v_cvt_pk_bf16_f32 v165, v11, v8
	global_load_dwordx4 v[10:13], v[4:5], off offset:32
	global_load_dwordx4 v[14:17], v[18:19], off offset:32
	s_waitcnt vmcnt(2)
	v_lshlrev_b32_e32 v20, 16, v166
	s_waitcnt vmcnt(1)
	v_mov_b32_e32 v22, v10
	s_waitcnt vmcnt(0)
	v_mov_b32_e32 v23, v14
	v_mov_b32_e32 v14, v11
	v_mov_b32_e32 v24, v12
	v_mov_b32_e32 v25, v16
	v_mov_b32_e32 v16, v13
	v_and_b32_e32 v21, 0xffff0000, v166
	v_lshlrev_b32_e32 v6, 16, v167
	v_and_b32_e32 v7, 0xffff0000, v167
	v_lshlrev_b32_e32 v10, 16, v168
	v_and_b32_e32 v11, 0xffff0000, v168
	v_lshlrev_b32_e32 v8, 16, v169
	v_and_b32_e32 v9, 0xffff0000, v169
	v_pk_mul_f32 v[12:13], v[22:23], s[6:7] op_sel_hi:[1,0]
	v_pk_mul_f32 v[14:15], v[14:15], s[6:7] op_sel_hi:[1,0]
	v_pk_mul_f32 v[22:23], v[24:25], s[6:7] op_sel_hi:[1,0]
	v_pk_mul_f32 v[16:17], v[16:17], s[6:7] op_sel_hi:[1,0]
	v_pk_mul_f32 v[24:25], v[12:13], v[20:21]
	v_pk_mul_f32 v[12:13], v[12:13], v[20:21] op_sel:[0,1] op_sel_hi:[1,0]
	v_pk_mul_f32 v[20:21], v[14:15], v[6:7]
	v_pk_mul_f32 v[6:7], v[14:15], v[6:7] op_sel:[0,1] op_sel_hi:[1,0]
	v_pk_mul_f32 v[14:15], v[22:23], v[10:11]
	v_pk_mul_f32 v[10:11], v[22:23], v[10:11] op_sel:[0,1] op_sel_hi:[1,0]
	v_pk_mul_f32 v[22:23], v[16:17], v[8:9]
	v_pk_mul_f32 v[8:9], v[16:17], v[8:9] op_sel:[0,1] op_sel_hi:[1,0]
	v_add_f32_e32 v12, v12, v13
	v_sub_f32_e32 v13, v20, v21
	v_add_f32_e32 v6, v6, v7
	v_sub_f32_e32 v7, v14, v15
	v_add_f32_e32 v10, v10, v11
	v_sub_f32_e32 v11, v22, v23
	v_add_f32_e32 v8, v8, v9
	v_sub_f32_e32 v1, v24, v25
	v_cvt_pk_bf16_f32 v166, v1, v12
	v_cvt_pk_bf16_f32 v167, v13, v6
	v_cvt_pk_bf16_f32 v168, v7, v10
	v_cvt_pk_bf16_f32 v169, v11, v8
	global_load_dwordx4 v[10:13], v[4:5], off offset:64
	global_load_dwordx4 v[14:17], v[18:19], off offset:64
	s_waitcnt vmcnt(2)
	v_lshlrev_b32_e32 v20, 16, v170
	s_waitcnt vmcnt(1)
	v_mov_b32_e32 v22, v10
	s_waitcnt vmcnt(0)
; __device__ __forceinline__ float bf2f(unsigned h) { return __uint_as_float(h << 16); }
; __device__ __forceinline__ void qkt192n(f32x16& p0, f32x16& p1, const char* Ks, const char* Kr, const bf16x8* qr, const f32x16& negm, int r32, int hi) {
; #pragma unroll
;   for (int d0 = 0; d0 < 8; ++d0) { const int cb = d0 * 32 + hi * 16;
;     const bf16x8 b0 = *reinterpret_cast<const bf16x8*>(Ks + KSWZ(r32, cb));
;     const bf16x8 b1 = *reinterpret_cast<const bf16x8*>(Ks + KSWZ(32 + r32, cb));
;     if (d0 == 0) { p0 = __builtin_amdgcn_mfma_f32_32x32x16_bf16(b0, qr[0], negm, 0, 0, 0); p1 = __builtin_amdgcn_mfma_f32_32x32x16_bf16(b1, qr[0], negm, 0, 0, 0); }
;     else { p0 = __builtin_amdgcn_mfma_f32_32x32x16_bf16(b0, qr[d0], p0, 0, 0, 0); p1 = __builtin_amdgcn_mfma_f32_32x32x16_bf16(b1, qr[d0], p1, 0, 0, 0); } }
; #pragma unroll
;   for (int d0 = 0; d0 < 4; ++d0) { const int cb = d0 * 32 + hi * 16;
;     const bf16x8 b0 = *reinterpret_cast<const bf16x8*>(Kr + RSWZ(r32, cb));
;     const bf16x8 b1 = *reinterpret_cast<const bf16x8*>(Kr + RSWZ(32 + r32, cb));
;     p0 = __builtin_amdgcn_mfma_f32_32x32x16_bf16(b0, qr[8 + d0], p0, 0, 0, 0);
;     p1 = __builtin_amdgcn_mfma_f32_32x32x16_bf16(b1, qr[8 + d0], p1, 0, 0, 0); }
; __device__ __forceinline__ void mla_unit(char* lds, const bf16_t* __restrict__ Qp, const bf16_t* __restrict__ Knp, const bf16_t* __restrict__ Vp, ...
;     ...
;     for (int d0 = 0; d0 < 4; ++d0) {
;       const u32x4 raw = *reinterpret_cast<const u32x4*>(Qw + 128 + d0 * 16);
;       const int i0 = d0 * 8 + hi * 4;
;       const f32x4 cc = *reinterpret_cast<const f32x4*>(cs_tab + pos * 32 + i0) * C, ss = *reinterpret_cast<const f32x4*>(sn_tab + pos * 32 + i0) * C;
;       u32x4 w;
; #pragma unroll
;       for (int p = 0; p < 4; ++p) { const float x1 = bf2f(raw[p] & 0xffffu), x2 = bf2f(raw[p] >> 16); w[p] = cvtpk(x1 * cc[p] - x2 * ss[p], x1 * ss[p] + x2 * cc[p]); }
;       qr[8 + d0] = *reinterpret_cast<bf16x8*>(&w);
;     } }
	v_mov_b32_e32 v23, v14
	v_mov_b32_e32 v14, v11
	v_mov_b32_e32 v24, v12
	v_mov_b32_e32 v25, v16
	v_mov_b32_e32 v16, v13
	v_and_b32_e32 v21, 0xffff0000, v170
	v_lshlrev_b32_e32 v6, 16, v171
	v_and_b32_e32 v7, 0xffff0000, v171
	v_lshlrev_b32_e32 v10, 16, v172
	v_and_b32_e32 v11, 0xffff0000, v172
	v_lshlrev_b32_e32 v8, 16, v173
	v_and_b32_e32 v9, 0xffff0000, v173
	v_pk_mul_f32 v[12:13], v[22:23], s[6:7] op_sel_hi:[1,0]
	v_pk_mul_f32 v[14:15], v[14:15], s[6:7] op_sel_hi:[1,0]
	v_pk_mul_f32 v[22:23], v[24:25], s[6:7] op_sel_hi:[1,0]
	v_pk_mul_f32 v[16:17], v[16:17], s[6:7] op_sel_hi:[1,0]
	v_pk_mul_f32 v[24:25], v[12:13], v[20:21]
	v_pk_mul_f32 v[12:13], v[12:13], v[20:21] op_sel:[0,1] op_sel_hi:[1,0]
	v_pk_mul_f32 v[20:21], v[14:15], v[6:7]
	v_pk_mul_f32 v[6:7], v[14:15], v[6:7] op_sel:[0,1] op_sel_hi:[1,0]
	v_pk_mul_f32 v[14:15], v[22:23], v[10:11]
	v_pk_mul_f32 v[10:11], v[22:23], v[10:11] op_sel:[0,1] op_sel_hi:[1,0]
	v_pk_mul_f32 v[22:23], v[16:17], v[8:9]
	v_pk_mul_f32 v[8:9], v[16:17], v[8:9] op_sel:[0,1] op_sel_hi:[1,0]
	v_sub_f32_e32 v1, v24, v25
	v_add_f32_e32 v12, v12, v13
	v_sub_f32_e32 v13, v20, v21
	v_add_f32_e32 v6, v6, v7
	v_sub_f32_e32 v7, v14, v15
	v_add_f32_e32 v10, v10, v11
	v_sub_f32_e32 v11, v22, v23
	v_add_f32_e32 v8, v8, v9
	v_cvt_pk_bf16_f32 v170, v1, v12
	v_cvt_pk_bf16_f32 v171, v13, v6
	v_cvt_pk_bf16_f32 v172, v7, v10
	v_cvt_pk_bf16_f32 v173, v11, v8
	global_load_dwordx4 v[36:39], v[4:5], off offset:96
	global_load_dwordx4 v[40:43], v[18:19], off offset:96
	v_mov_b32_e32 v14, v0
	v_mov_b32_e32 v15, v0
	v_mov_b32_e32 v1, v0
	v_mov_b32_e32 v2, v0
	v_mov_b32_e32 v3, v0
	v_mov_b32_e32 v4, v0
	v_mov_b32_e32 v5, v0
	v_mov_b32_e32 v6, v0
	v_mov_b32_e32 v7, v0
	v_mov_b32_e32 v8, v0
	v_mov_b32_e32 v9, v0
	v_mov_b32_e32 v10, v0
	v_mov_b32_e32 v11, v0
	v_mov_b32_e32 v12, v0
	v_mov_b32_e32 v13, v0
	v_mov_b64_e32 v[30:31], v[14:15]
	v_mov_b64_e32 v[28:29], v[12:13]
	v_mov_b64_e32 v[26:27], v[10:11]
	v_mov_b64_e32 v[24:25], v[8:9]
	v_mov_b64_e32 v[22:23], v[6:7]
	v_mov_b64_e32 v[20:21], v[4:5]
	v_mov_b64_e32 v[18:19], v[2:3]
	v_mov_b64_e32 v[16:17], v[0:1]
	s_waitcnt vmcnt(2)
	v_lshlrev_b32_e32 v44, 16, v174
	s_waitcnt vmcnt(1)
	v_mov_b32_e32 v46, v36
	s_waitcnt vmcnt(0)
	v_mov_b32_e32 v47, v40
	v_mov_b32_e32 v40, v37
	v_mov_b32_e32 v52, v38
	v_mov_b32_e32 v53, v42
	v_mov_b32_e32 v42, v39
	v_and_b32_e32 v45, 0xffff0000, v174
	v_lshlrev_b32_e32 v32, 16, v175
	v_and_b32_e32 v33, 0xffff0000, v175
	v_lshlrev_b32_e32 v36, 16, v176
	v_and_b32_e32 v37, 0xffff0000, v176
	v_lshlrev_b32_e32 v34, 16, v177
	v_and_b32_e32 v35, 0xffff0000, v177
	v_pk_mul_f32 v[38:39], v[46:47], s[6:7] op_sel_hi:[1,0]
	v_pk_mul_f32 v[40:41], v[40:41], s[6:7] op_sel_hi:[1,0]
	v_pk_mul_f32 v[46:47], v[52:53], s[6:7] op_sel_hi:[1,0]
	v_pk_mul_f32 v[42:43], v[42:43], s[6:7] op_sel_hi:[1,0]
	v_pk_mul_f32 v[52:53], v[38:39], v[44:45]
	v_pk_mul_f32 v[38:39], v[38:39], v[44:45] op_sel:[0,1] op_sel_hi:[1,0]
	v_pk_mul_f32 v[44:45], v[40:41], v[32:33]
	v_pk_mul_f32 v[32:33], v[40:41], v[32:33] op_sel:[0,1] op_sel_hi:[1,0]
	v_pk_mul_f32 v[40:41], v[46:47], v[36:37]
	v_pk_mul_f32 v[36:37], v[46:47], v[36:37] op_sel:[0,1] op_sel_hi:[1,0]
	v_pk_mul_f32 v[46:47], v[42:43], v[34:35]
	v_pk_mul_f32 v[34:35], v[42:43], v[34:35] op_sel:[0,1] op_sel_hi:[1,0]
	v_sub_f32_e32 v42, v52, v53
	v_add_f32_e32 v38, v38, v39
	v_sub_f32_e32 v39, v44, v45
	v_add_f32_e32 v32, v32, v33
	v_sub_f32_e32 v33, v40, v41
	v_add_f32_e32 v36, v36, v37
	v_sub_f32_e32 v37, v46, v47
	v_add_f32_e32 v34, v34, v35
	v_cvt_pk_bf16_f32 v174, v42, v38
	v_cvt_pk_bf16_f32 v175, v39, v32
	v_cvt_pk_bf16_f32 v176, v33, v36
	v_cvt_pk_bf16_f32 v177, v37, v34
	s_waitcnt vmcnt(10) lgkmcnt(0)
	s_barrier
	ds_read_b128 v[52:55], v56 offset:49152
	ds_read_b128 v[56:59], v56 offset:57344
	s_waitcnt lgkmcnt(1)
	v_mfma_f32_32x32x16_bf16 v[32:47], v[52:55], v[130:133], v[16:31]
	v_or_b32_e32 v52, 32, v194
	v_xad_u32 v53, v52, v51, v66
	s_waitcnt lgkmcnt(0)
	v_mfma_f32_32x32x16_bf16 v[16:31], v[56:59], v[130:133], v[16:31]
	ds_read_b128 v[54:57], v53 offset:49152
	ds_read_b128 v[58:61], v53 offset:57344
	v_or_b32_e32 v53, 64, v194
	v_xad_u32 v62, v53, v51, v66
	s_waitcnt lgkmcnt(1)
	v_mfma_f32_32x32x16_bf16 v[32:47], v[54:57], v[134:137], v[32:47]
	s_waitcnt lgkmcnt(0)
	v_mfma_f32_32x32x16_bf16 v[16:31], v[58:61], v[134:137], v[16:31]
	ds_read_b128 v[54:57], v62 offset:49152
	ds_read_b128 v[58:61], v62 offset:57344
	s_waitcnt lgkmcnt(1)
	v_mfma_f32_32x32x16_bf16 v[32:47], v[54:57], v[138:141], v[32:47]
	v_or_b32_e32 v54, 0x60, v194
	v_xad_u32 v55, v54, v51, v66
	s_waitcnt lgkmcnt(0)
	v_mfma_f32_32x32x16_bf16 v[16:31], v[58:61], v[138:141], v[16:31]
	ds_read_b128 v[56:59], v55 offset:49152
	ds_read_b128 v[60:63], v55 offset:57344
	v_or_b32_e32 v55, 0x80, v194
	v_xad_u32 v64, v55, v51, v66
	s_waitcnt lgkmcnt(1)
	v_mfma_f32_32x32x16_bf16 v[32:47], v[56:59], v[142:145], v[32:47]
	s_waitcnt lgkmcnt(0)
	v_mfma_f32_32x32x16_bf16 v[16:31], v[60:63], v[142:145], v[16:31]
	ds_read_b128 v[56:59], v64 offset:49152
	ds_read_b128 v[60:63], v64 offset:57344
	s_waitcnt lgkmcnt(1)
	v_mfma_f32_32x32x16_bf16 v[32:47], v[56:59], v[154:157], v[32:47]
	v_or_b32_e32 v56, 0xa0, v194
	v_xad_u32 v57, v56, v51, v66
	s_waitcnt lgkmcnt(0)
	v_mfma_f32_32x32x16_bf16 v[16:31], v[60:63], v[154:157], v[16:31]
	ds_read_b128 v[58:61], v57 offset:49152
	ds_read_b128 v[62:65], v57 offset:57344
	v_or_b32_e32 v57, 0xc0, v194
	v_xad_u32 v67, v57, v51, v66
	s_waitcnt lgkmcnt(1)
	v_mfma_f32_32x32x16_bf16 v[32:47], v[58:61], v[150:153], v[32:47]
	s_waitcnt lgkmcnt(0)
	v_mfma_f32_32x32x16_bf16 v[16:31], v[62:65], v[150:153], v[16:31]
	ds_read_b128 v[58:61], v67 offset:49152
	ds_read_b128 v[62:65], v67 offset:57344
	s_waitcnt lgkmcnt(1)
; __device__ __forceinline__ void qkt192n(f32x16& p0, f32x16& p1, const char* Ks, const char* Kr, const bf16x8* qr, const f32x16& negm, int r32, int hi) {
; #pragma unroll
;   for (int d0 = 0; d0 < 8; ++d0) { const int cb = d0 * 32 + hi * 16;
;     const bf16x8 b0 = *reinterpret_cast<const bf16x8*>(Ks + KSWZ(r32, cb));
;     const bf16x8 b1 = *reinterpret_cast<const bf16x8*>(Ks + KSWZ(32 + r32, cb));
;     if (d0 == 0) { p0 = __builtin_amdgcn_mfma_f32_32x32x16_bf16(b0, qr[0], negm, 0, 0, 0); p1 = __builtin_amdgcn_mfma_f32_32x32x16_bf16(b1, qr[0], negm, 0, 0, 0); }
;     else { p0 = __builtin_amdgcn_mfma_f32_32x32x16_bf16(b0, qr[d0], p0, 0, 0, 0); p1 = __builtin_amdgcn_mfma_f32_32x32x16_bf16(b1, qr[d0], p1, 0, 0, 0); } }
; #pragma unroll
;   for (int d0 = 0; d0 < 4; ++d0) { const int cb = d0 * 32 + hi * 16;
;     const bf16x8 b0 = *reinterpret_cast<const bf16x8*>(Kr + RSWZ(r32, cb));
;     const bf16x8 b1 = *reinterpret_cast<const bf16x8*>(Kr + RSWZ(32 + r32, cb));
;     p0 = __builtin_amdgcn_mfma_f32_32x32x16_bf16(b0, qr[8 + d0], p0, 0, 0, 0);
;     p1 = __builtin_amdgcn_mfma_f32_32x32x16_bf16(b1, qr[8 + d0], p1, 0, 0, 0); }
	v_mfma_f32_32x32x16_bf16 v[32:47], v[58:61], v[146:149], v[32:47]
	v_or_b32_e32 v58, 0xe0, v194
	v_xad_u32 v59, v58, v51, v66
	s_waitcnt lgkmcnt(0)
	v_mfma_f32_32x32x16_bf16 v[16:31], v[62:65], v[146:149], v[16:31]
	ds_read_b128 v[60:63], v59 offset:49152
	ds_read_b128 v[64:67], v59 offset:57344
	v_lshlrev_b32_e32 v59, 3, v50
	v_and_b32_e32 v68, 0x70, v59
	v_xad_u32 v69, v194, v68, v206
	v_and_b32_e32 v50, 63, v50
	v_cmp_gt_u32_e64 s[40:41], 32, v50
	s_waitcnt lgkmcnt(1)
	v_mfma_f32_32x32x16_bf16 v[32:47], v[60:63], v[158:161], v[32:47]
	s_waitcnt lgkmcnt(0)
	v_mfma_f32_32x32x16_bf16 v[16:31], v[64:67], v[158:161], v[16:31]
	ds_read_b128 v[60:63], v69
	ds_read_b128 v[64:67], v69 offset:4096
	v_xad_u32 v69, v52, v68, v206
	s_waitcnt lgkmcnt(1)
	v_mfma_f32_32x32x16_bf16 v[32:47], v[60:63], v[162:165], v[32:47]
	s_waitcnt lgkmcnt(0)
	v_mfma_f32_32x32x16_bf16 v[16:31], v[64:67], v[162:165], v[16:31]
	ds_read_b128 v[60:63], v69
	ds_read_b128 v[64:67], v69 offset:4096
	v_xad_u32 v69, v53, v68, v206
	v_xad_u32 v68, v54, v68, v206
	s_waitcnt lgkmcnt(1)
	v_mfma_f32_32x32x16_bf16 v[32:47], v[60:63], v[166:169], v[32:47]
	s_waitcnt lgkmcnt(0)
	v_mfma_f32_32x32x16_bf16 v[16:31], v[64:67], v[166:169], v[16:31]
	ds_read_b128 v[60:63], v69
	ds_read_b128 v[64:67], v69 offset:4096
	s_waitcnt lgkmcnt(1)
	v_mfma_f32_32x32x16_bf16 v[32:47], v[60:63], v[170:173], v[32:47]
	s_waitcnt lgkmcnt(0)
	v_mfma_f32_32x32x16_bf16 v[16:31], v[64:67], v[170:173], v[16:31]
	ds_read_b128 v[60:63], v68
	ds_read_b128 v[64:67], v68 offset:4096
	s_waitcnt lgkmcnt(1)
	v_mfma_f32_32x32x16_bf16 v[32:47], v[60:63], v[174:177], v[32:47]
	s_waitcnt lgkmcnt(0)
	v_mfma_f32_32x32x16_bf16 v[16:31], v[64:67], v[174:177], v[16:31]
	s_nop 9
	v_max_f32_e32 v60, v33, v33
	v_max_f32_e32 v61, v32, v32
	v_max_f32_e32 v60, v61, v60
	v_max3_f32 v62, v34, v35, v17
	v_max3_f32 v60, v60, v16, v18
	v_max3_f32 v61, v62, v38, v39
	v_max3_f32 v60, v60, v19, v36
	v_max3_f32 v61, v61, v22, v23
	v_max3_f32 v60, v60, v37, v20
	v_max3_f32 v61, v61, v42, v43
	v_max3_f32 v60, v60, v21, v40
	v_max3_f32 v61, v61, v26, v27
	v_max3_f32 v60, v60, v41, v24
	v_max3_f32 v61, v61, v46, v47
	v_max3_f32 v60, v60, v25, v44
	v_max3_f32 v61, v61, v30, v31
	v_max3_f32 v60, v60, v45, v28
	v_max3_f32 v60, v60, v29, v61
	v_mov_b32_e32 v61, v60
	s_nop 1
	v_permlane32_swap_b32_e32 v60, v61
	v_max_f32_e32 v61, v61, v61
	v_max_f32_e32 v60, v60, v60
	v_max_f32_e32 v61, v60, v61
	v_exp_f32_e64 v60, -v61
	v_add_f32_e32 v203, 0, v61
	v_xor_b32_e32 v66, 0x80000000, v203
	v_mov_b32_e32 v67, v66
	v_mov_b32_e32 v68, v66
	v_mov_b32_e32 v69, v66
	v_mov_b32_e32 v70, v66
	v_mov_b32_e32 v71, v66
	v_mov_b32_e32 v72, v66
	v_mov_b32_e32 v73, v66
	v_mov_b32_e32 v74, v66
	v_mov_b32_e32 v75, v66
	v_mov_b32_e32 v76, v66
	v_mov_b32_e32 v77, v66
	v_mov_b32_e32 v78, v66
	v_mov_b32_e32 v79, v66
	v_mov_b32_e32 v80, v66
	v_mov_b32_e32 v81, v66
	s_and_saveexec_b64 s[6:7], s[40:41]
	ds_write_b32 v200, v60 offset:128
	s_or_b64 exec, exec, s[6:7]
	v_sub_f32_e32 v32, v32, v61
	v_sub_f32_e32 v33, v33, v61
	v_sub_f32_e32 v82, v16, v61
	v_exp_f32_e32 v16, v32
	v_sub_f32_e32 v34, v34, v61
	v_sub_f32_e32 v83, v17, v61
	v_exp_f32_e32 v17, v33
	v_sub_f32_e32 v35, v35, v61
	v_sub_f32_e32 v84, v18, v61
	v_exp_f32_e32 v18, v34
	v_sub_f32_e32 v36, v36, v61
	v_sub_f32_e32 v85, v19, v61
	v_exp_f32_e32 v19, v35
	v_sub_f32_e32 v37, v37, v61
	v_sub_f32_e32 v86, v20, v61
	v_exp_f32_e32 v20, v36
	v_add_f32_e32 v32, 0, v16
	v_sub_f32_e32 v38, v38, v61
	v_sub_f32_e32 v87, v21, v61
	v_exp_f32_e32 v21, v37
	v_add_f32_e32 v32, v17, v32
	v_sub_f32_e32 v39, v39, v61
	v_sub_f32_e32 v88, v22, v61
	v_exp_f32_e32 v22, v38
	v_add_f32_e32 v32, v18, v32
	v_sub_f32_e32 v40, v40, v61
	v_sub_f32_e32 v89, v23, v61
	v_exp_f32_e32 v23, v39
	v_add_f32_e32 v32, v19, v32
	v_sub_f32_e32 v41, v41, v61
	v_sub_f32_e32 v90, v24, v61
	v_exp_f32_e32 v24, v40
	v_add_f32_e32 v32, v20, v32
	v_sub_f32_e32 v42, v42, v61
	v_sub_f32_e32 v91, v25, v61
	v_exp_f32_e32 v25, v41
	v_add_f32_e32 v32, v21, v32
	v_sub_f32_e32 v43, v43, v61
	v_sub_f32_e32 v92, v26, v61
	v_exp_f32_e32 v26, v42
	v_add_f32_e32 v32, v22, v32
	v_sub_f32_e32 v44, v44, v61
	v_sub_f32_e32 v93, v27, v61
	v_exp_f32_e32 v27, v43
	v_add_f32_e32 v32, v23, v32
	v_sub_f32_e32 v45, v45, v61
	v_sub_f32_e32 v94, v28, v61
	v_exp_f32_e32 v28, v44
	v_add_f32_e32 v32, v24, v32
	s_lshr_b32 s69, s74, 5
	v_sub_f32_e32 v46, v46, v61
	v_sub_f32_e32 v95, v29, v61
	v_exp_f32_e32 v29, v45
	v_add_f32_e32 v32, v25, v32
	v_sub_f32_e32 v47, v47, v61
	v_sub_f32_e32 v96, v30, v61
	s_and_b32 s0, s69, 15
	v_exp_f32_e32 v30, v46
	v_add_f32_e32 v32, v26, v32
	s_movk_i32 s1, 0x70
	v_sub_f32_e32 v97, v31, v61
	s_lshl_b32 s0, s0, 23
	v_exp_f32_e32 v31, v47
	v_add_f32_e32 v32, v27, v32
	v_bitop3_b32 v221, v194, v59, s1 bitop3:0x78
	v_bitop3_b32 v209, v52, v59, s1 bitop3:0x78
	v_bitop3_b32 v208, v53, v59, s1 bitop3:0x78
	v_bitop3_b32 v207, v54, v59, s1 bitop3:0x78
	v_readlane_b32 s1, v254, 9
	v_lshlrev_b32_e32 v62, 4, v50
	v_add_f32_e32 v32, v28, v32
	s_add_u32 s36, s1, s36
	v_readlane_b32 s1, v254, 10
	v_lshlrev_b32_e32 v195, 2, v49
	v_lshlrev_b32_e32 v49, 3, v50
	v_and_b32_e32 v62, 0xc0, v62
	v_lshlrev_b32_e32 v50, 1, v50
	v_add_f32_e32 v32, v29, v32
	s_addc_u32 s37, s1, s37
	v_and_or_b32 v62, v49, 24, v62
	v_and_b32_e32 v50, 32, v50
	v_and_b32_e32 v49, 0x100, v49
	v_add_f32_e32 v32, v30, v32
	s_add_u32 s0, s0, s30
	v_or3_b32 v201, v62, v50, v49
	v_mul_f32_e32 v234, 0, v60
	v_add_f32_e32 v186, v31, v32
	v_cvt_pk_bf16_f32 v182, v16, v17
	v_cvt_pk_bf16_f32 v183, v18, v19
	v_cvt_pk_bf16_f32 v184, v20, v21
	v_cvt_pk_bf16_f32 v185, v22, v23
	v_cvt_pk_bf16_f32 v178, v24, v25
	v_cvt_pk_bf16_f32 v179, v26, v27
	v_cvt_pk_bf16_f32 v180, v28, v29
	v_cvt_pk_bf16_f32 v181, v30, v31
	v_bitop3_b32 v229, v194, v48, s53 bitop3:0x78
	v_bitop3_b32 v230, v194, v204, v51 bitop3:0xde
	v_bitop3_b32 v228, v52, v48, s53 bitop3:0x78
	v_bitop3_b32 v231, v52, v204, v51 bitop3:0xde
	v_bitop3_b32 v227, v53, v48, s53 bitop3:0x78
	v_bitop3_b32 v226, v54, v48, s53 bitop3:0x78
	v_bitop3_b32 v225, v55, v48, s53 bitop3:0x78
	v_bitop3_b32 v224, v56, v48, s53 bitop3:0x78
	v_bitop3_b32 v223, v57, v48, s53 bitop3:0x78
	v_bitop3_b32 v222, v58, v48, s53 bitop3:0x78
	s_addc_u32 s1, 0, s31
	v_readlane_b32 s12, v254, 35
	v_mov_b64_e32 v[64:65], v[14:15]
	v_mov_b64_e32 v[48:49], v[14:15]
	v_mov_b64_e32 v[32:33], v[14:15]
	v_readlane_b32 s13, v254, 36
	s_add_u32 s30, s12, s0
	v_mov_b64_e32 v[62:63], v[12:13]
	v_mov_b64_e32 v[60:61], v[10:11]
	v_mov_b64_e32 v[58:59], v[8:9]
	v_mov_b64_e32 v[56:57], v[6:7]
	v_mov_b64_e32 v[54:55], v[4:5]
	v_mov_b64_e32 v[52:53], v[2:3]
	v_mov_b64_e32 v[50:51], v[0:1]
	v_mov_b64_e32 v[46:47], v[12:13]
	v_mov_b64_e32 v[44:45], v[10:11]
	v_mov_b64_e32 v[42:43], v[8:9]
	v_mov_b64_e32 v[40:41], v[6:7]
	v_mov_b64_e32 v[38:39], v[4:5]
	v_mov_b64_e32 v[36:37], v[2:3]
	v_mov_b64_e32 v[34:35], v[0:1]
	v_mov_b64_e32 v[30:31], v[12:13]
	v_mov_b64_e32 v[28:29], v[10:11]
	v_mov_b64_e32 v[26:27], v[8:9]
	v_mov_b64_e32 v[24:25], v[6:7]
	v_mov_b64_e32 v[22:23], v[4:5]
	v_mov_b64_e32 v[20:21], v[2:3]
	v_mov_b64_e32 v[18:19], v[0:1]
	v_mov_b64_e32 v[16:17], v[14:15]
	s_mov_b32 s70, 1
	v_add_u32_e32 v202, 0, v201
	v_permlane32_swap_b32_e32 v182, v184
	v_permlane32_swap_b32_e32 v183, v185
	v_permlane32_swap_b32_e32 v178, v180
	v_permlane32_swap_b32_e32 v179, v181
	s_mov_b32 s77, 2
	v_add_u32_e32 v232, v229, v204
	v_add_u32_e32 v233, v228, v204
	s_addc_u32 s31, s13, s1
	s_mov_b32 s78, 0
	v_mov_b64_e32 v[14:15], v[12:13]
	v_mov_b64_e32 v[12:13], v[10:11]
	v_mov_b64_e32 v[10:11], v[8:9]
	v_mov_b64_e32 v[8:9], v[6:7]
	v_mov_b64_e32 v[6:7], v[4:5]
	v_mov_b64_e32 v[4:5], v[2:3]
	v_mov_b64_e32 v[2:3], v[0:1]
	s_mov_b32 s0, 0
	v_readlane_b32 s14, v254, 37
	v_readlane_b32 s15, v254, 38
	.p2alignl 6, 3212836864

; template <class Epi, class Sched, bool ALIGN_EPI = false, bool SP2 = false>
; __device__ __forceinline__ void gemm_phase(PG8_LAS unsigned char* lds, const Gemm g, const Sched& S, const Epi& E) {
;     ...
;         const bool has_next = S.next(ui + 1, nxt);
;         const char* nA = has_next ? (const char*)g.A + (size_t)nxt.pm * tstepB : cA; const char* nB = has_next ? (const char*)g.Bt + (size_t)nxt.pn * tstepB : cB;
;     ...
; #pragma unroll
;         for (int a = 0; a < 2; ++a)
; #pragma unroll
;             for (int b = 0; b < 2; ++b)
; #pragma unroll
;                 for (int m = 0; m < 4; ++m)
; #pragma unroll
;                     for (int n = 0; n < 2; ++n) acc[a][b][m][n] = (f32x4){0.f, 0.f, 0.f, 0.f};
.LBB0_371:
	s_ashr_i32 s71, s70, 31
	s_lshl_b64 s[8:9], s[70:71], 15
	s_add_u32 s94, s82, s8
	s_addc_u32 s95, s83, s9
	s_and_b64 s[8:9], s[40:41], exec
	s_cselect_b32 s59, s95, s75
	s_cselect_b32 s69, s94, s74
	s_ashr_i32 s73, s72, 31
	s_lshl_b64 s[8:9], s[72:73], 15
	s_add_u32 s88, s86, s8
	s_addc_u32 s89, s87, s9
	s_and_b64 s[8:9], s[40:41], exec
	s_cselect_b32 s9, s89, s7
	s_cselect_b32 s8, s88, s6
	s_add_u32 s76, s6, s58
	s_addc_u32 s77, s7, 0
	s_add_u32 s6, s74, 0x204000
	v_mov_b32_e32 v2, 0
	s_addc_u32 s7, s75, 0
	s_mov_b32 s71, 0
	v_mov_b32_e32 v3, v2
	v_mov_b32_e32 v4, v2
	v_mov_b32_e32 v5, v2
	v_mov_b32_e32 v6, v2
	v_mov_b32_e32 v7, v2
	v_mov_b32_e32 v8, v2
	v_mov_b32_e32 v9, v2
	v_mov_b32_e32 v18, v2
	v_mov_b32_e32 v19, v2
	v_mov_b32_e32 v20, v2
	v_mov_b32_e32 v21, v2
	v_mov_b32_e32 v22, v2
	v_mov_b32_e32 v23, v2
	v_mov_b32_e32 v24, v2
	v_mov_b32_e32 v25, v2
	v_mov_b32_e32 v34, v2
	v_mov_b32_e32 v35, v2
	v_mov_b32_e32 v36, v2
	v_mov_b32_e32 v37, v2
	v_mov_b32_e32 v38, v2
	v_mov_b32_e32 v39, v2
	v_mov_b32_e32 v40, v2
	v_mov_b32_e32 v41, v2
	v_mov_b32_e32 v50, v2
	v_mov_b32_e32 v51, v2
	v_mov_b32_e32 v52, v2
	v_mov_b32_e32 v53, v2
	v_mov_b32_e32 v54, v2
	v_mov_b32_e32 v55, v2
	v_mov_b32_e32 v56, v2
	v_mov_b32_e32 v57, v2
	v_mov_b32_e32 v10, v2
	v_mov_b32_e32 v11, v2
	v_mov_b32_e32 v12, v2
	v_mov_b32_e32 v13, v2
	v_mov_b32_e32 v14, v2
	v_mov_b32_e32 v15, v2
	v_mov_b32_e32 v16, v2
	v_mov_b32_e32 v17, v2
	v_mov_b32_e32 v26, v2
	v_mov_b32_e32 v27, v2
	v_mov_b32_e32 v28, v2
	v_mov_b32_e32 v29, v2
	v_mov_b32_e32 v30, v2
	v_mov_b32_e32 v31, v2
	v_mov_b32_e32 v32, v2
	v_mov_b32_e32 v33, v2
	v_mov_b32_e32 v42, v2
	v_mov_b32_e32 v43, v2
	v_mov_b32_e32 v44, v2
	v_mov_b32_e32 v45, v2
	v_mov_b32_e32 v46, v2
	v_mov_b32_e32 v47, v2
	v_mov_b32_e32 v48, v2
	v_mov_b32_e32 v49, v2
	v_mov_b32_e32 v58, v2
	v_mov_b32_e32 v59, v2
	v_mov_b32_e32 v60, v2
	v_mov_b32_e32 v61, v2
	v_mov_b32_e32 v62, v2
	v_mov_b32_e32 v63, v2
	v_mov_b32_e32 v64, v2
	v_mov_b32_e32 v65, v2
	v_mov_b32_e32 v66, v2
	v_mov_b32_e32 v67, v2
	v_mov_b32_e32 v68, v2
	v_mov_b32_e32 v69, v2
	v_mov_b32_e32 v70, v2
	v_mov_b32_e32 v71, v2
	v_mov_b32_e32 v72, v2
	v_mov_b32_e32 v73, v2
	v_mov_b32_e32 v78, v2
	v_mov_b32_e32 v79, v2
	v_mov_b32_e32 v80, v2
	v_mov_b32_e32 v81, v2
	v_mov_b32_e32 v86, v2
	v_mov_b32_e32 v87, v2
	v_mov_b32_e32 v88, v2
	v_mov_b32_e32 v89, v2
	v_mov_b32_e32 v94, v2
	v_mov_b32_e32 v95, v2
	v_mov_b32_e32 v96, v2
	v_mov_b32_e32 v97, v2
	v_mov_b32_e32 v102, v2
	v_mov_b32_e32 v103, v2
	v_mov_b32_e32 v104, v2
	v_mov_b32_e32 v105, v2
	v_mov_b32_e32 v110, v2
	v_mov_b32_e32 v111, v2
	v_mov_b32_e32 v112, v2
	v_mov_b32_e32 v113, v2
	v_mov_b32_e32 v118, v2
	v_mov_b32_e32 v119, v2
	v_mov_b32_e32 v120, v2
	v_mov_b32_e32 v121, v2
	v_mov_b32_e32 v74, v2
	v_mov_b32_e32 v75, v2
	v_mov_b32_e32 v76, v2
	v_mov_b32_e32 v77, v2
	v_mov_b32_e32 v82, v2
	v_mov_b32_e32 v83, v2
	v_mov_b32_e32 v84, v2
	v_mov_b32_e32 v85, v2
	v_mov_b32_e32 v90, v2
	v_mov_b32_e32 v91, v2
	v_mov_b32_e32 v92, v2
	v_mov_b32_e32 v93, v2
	v_mov_b32_e32 v98, v2
	v_mov_b32_e32 v99, v2
	v_mov_b32_e32 v100, v2
	v_mov_b32_e32 v101, v2
	v_mov_b32_e32 v106, v2
	v_mov_b32_e32 v107, v2
	v_mov_b32_e32 v108, v2
	v_mov_b32_e32 v109, v2
	v_mov_b32_e32 v114, v2
	v_mov_b32_e32 v115, v2
	v_mov_b32_e32 v116, v2
	v_mov_b32_e32 v117, v2
	v_mov_b32_e32 v122, v2
	v_mov_b32_e32 v123, v2
	v_mov_b32_e32 v124, v2
	v_mov_b32_e32 v125, v2
	v_mov_b32_e32 v126, v2
	v_mov_b32_e32 v127, v2
	v_mov_b32_e32 v128, v2
	v_mov_b32_e32 v129, v2
	s_branch .LBB0_373
	.p2alignl 6, 3212836864
